# v053 + hand-written grid barrier for all later seams: workgroups wait on the cross-XCC arrival counter directly (no generation words)
# speedup vs baseline: 1.0112x; 1.0025x over previous
.LBB0_262:
	s_load_dwordx2 s[6:7], s[0:1], 0x150
	v_readlane_b32 s4, v251, 38
	s_or_b32 s4, s4, 2
	s_waitcnt lgkmcnt(0)
	s_cmp_ge_i32 s4, s7
	s_cbranch_scc1 .LBB0_312
	s_waitcnt vmcnt(0)
	s_barrier
	s_mov_b64 s[16:17], exec
	v_readlane_b32 s6, v251, 22
	v_readlane_b32 s7, v251, 23
	s_and_b64 s[6:7], s[16:17], s[6:7]
	s_mov_b64 exec, s[6:7]
	s_cbranch_execz .LBB0_311
	s_waitcnt vmcnt(0) lgkmcnt(0)
	v_mov_b32_e32 v2, 0x22020
	ds_read_b64 v[4:5], v2
	v_readlane_b32 s6, v252, 35
	v_readlane_b32 s7, v252, 36
	v_readlane_b32 s8, v252, 39
	v_readlane_b32 s9, v252, 40
	v_mov_b32_e32 v6, 1
	s_nop 4
	global_atomic_add v6, v3, v6, s[6:7] sc0
	s_waitcnt vmcnt(0) lgkmcnt(0)
	v_cvt_f32_u32_e32 v7, v6
	v_cvt_f32_u32_e32 v8, v4
	v_add_f32_e32 v7, 0.5, v7
	v_rcp_f32_e32 v8, v8
	s_nop 1
	v_mul_f32_e32 v7, v7, v8
	v_cvt_u32_f32_e32 v7, v7
	v_mad_u32_u24 v8, v7, v4, v4
	v_mad_u32_u24 v9, v7, v5, v5
	v_add_u32_e32 v6, 1, v6
	v_cmp_eq_u32_e32 vcc, v6, v8
	s_cbranch_vccz .Lxb_poll_0
	buffer_wbl2 sc1
	s_waitcnt vmcnt(0)
	v_mov_b32_e32 v6, 1
	global_atomic_add v3, v6, s[8:9]
.Lxb_poll_0:
	s_mov_b32 s5, 0
.Lxb_spin_0:
	global_load_dword v7, v3, s[8:9] sc1
	s_waitcnt vmcnt(0)
	v_cmp_ge_u32_e32 vcc, v7, v9
	s_cbranch_vccnz .Lxb_done_0
	s_sleep 1
	s_add_u32 s5, s5, 1
	s_cmp_lt_u32 s5, 0x40000
	s_cbranch_scc1 .Lxb_spin_0
.Lxb_done_0:
	buffer_inv sc1
	s_waitcnt vmcnt(0)

.LBB0_828:
	s_load_dwordx2 s[6:7], s[0:1], 0x150
	v_readlane_b32 s4, v251, 38
	s_or_b32 s4, s4, 3
	s_waitcnt lgkmcnt(0)
	s_cmp_ge_i32 s4, s7
	s_cbranch_scc1 .LBB0_878
	s_waitcnt vmcnt(0)
	s_waitcnt vmcnt(0)
	s_barrier
	s_mov_b64 s[16:17], exec
	v_readlane_b32 s6, v251, 22
	v_readlane_b32 s7, v251, 23
	s_and_b64 s[6:7], s[16:17], s[6:7]
	s_mov_b64 exec, s[6:7]
	s_cbranch_execz .LBB0_877
	s_waitcnt vmcnt(0) lgkmcnt(0)
	v_mov_b32_e32 v2, 0x22020
	ds_read_b64 v[4:5], v2
	v_readlane_b32 s6, v252, 35
	v_readlane_b32 s7, v252, 36
	v_readlane_b32 s8, v252, 39
	v_readlane_b32 s9, v252, 40
	v_mov_b32_e32 v6, 1
	s_nop 4
	global_atomic_add v6, v3, v6, s[6:7] sc0
	s_waitcnt vmcnt(0) lgkmcnt(0)
	v_cvt_f32_u32_e32 v7, v6
	v_cvt_f32_u32_e32 v8, v4
	v_add_f32_e32 v7, 0.5, v7
	v_rcp_f32_e32 v8, v8
	s_nop 1
	v_mul_f32_e32 v7, v7, v8
	v_cvt_u32_f32_e32 v7, v7
	v_mad_u32_u24 v8, v7, v4, v4
	v_mad_u32_u24 v9, v7, v5, v5
	v_add_u32_e32 v6, 1, v6
	v_cmp_eq_u32_e32 vcc, v6, v8
	s_cbranch_vccz .Lxb_poll_1
	buffer_wbl2 sc1
	s_waitcnt vmcnt(0)
	v_mov_b32_e32 v6, 1
	global_atomic_add v3, v6, s[8:9]

.LBB0_1216:
	s_load_dwordx2 s[6:7], s[0:1], 0x150
	v_readlane_b32 s4, v251, 38
	s_add_i32 s4, s4, 4
	s_waitcnt lgkmcnt(0)
	s_cmp_ge_i32 s4, s7
	s_cbranch_scc1 .LBB0_1266
	s_waitcnt vmcnt(0)
	s_waitcnt vmcnt(63) expcnt(7) lgkmcnt(15)
	s_barrier
	s_mov_b64 s[16:17], exec
	v_readlane_b32 s6, v251, 22
	v_readlane_b32 s7, v251, 23
	s_and_b64 s[6:7], s[16:17], s[6:7]
	s_mov_b64 exec, s[6:7]
	s_cbranch_execz .LBB0_1265
	s_waitcnt vmcnt(0) lgkmcnt(0)
	v_mov_b32_e32 v2, 0x22020
	ds_read_b64 v[4:5], v2
	v_readlane_b32 s6, v252, 35
	v_readlane_b32 s7, v252, 36
	v_readlane_b32 s8, v252, 39
	v_readlane_b32 s9, v252, 40
	v_mov_b32_e32 v6, 1
	s_nop 4
	global_atomic_add v6, v3, v6, s[6:7] sc0
	s_waitcnt vmcnt(0) lgkmcnt(0)
	v_cvt_f32_u32_e32 v7, v6
	v_cvt_f32_u32_e32 v8, v4
	v_add_f32_e32 v7, 0.5, v7
	v_rcp_f32_e32 v8, v8
	s_nop 1
	v_mul_f32_e32 v7, v7, v8
	v_cvt_u32_f32_e32 v7, v7
	v_mad_u32_u24 v8, v7, v4, v4
	v_mad_u32_u24 v9, v7, v5, v5
	v_add_u32_e32 v6, 1, v6
	v_cmp_eq_u32_e32 vcc, v6, v8
	s_cbranch_vccz .Lxb_poll_2
	buffer_wbl2 sc1
	s_waitcnt vmcnt(0)
	v_mov_b32_e32 v6, 1
	global_atomic_add v3, v6, s[8:9]

.LBB0_1281:
	s_or_b64 exec, exec, s[16:17]
	s_load_dwordx2 s[6:7], s[0:1], 0x150
	v_readlane_b32 s4, v251, 38
	s_add_i32 s4, s4, 5
	s_waitcnt lgkmcnt(0)
	s_cmp_ge_i32 s4, s7
	s_cbranch_scc1 .LBB0_1331
	s_waitcnt vmcnt(0)
	s_barrier
	s_mov_b64 s[16:17], exec
	v_readlane_b32 s6, v251, 22
	v_readlane_b32 s7, v251, 23
	s_and_b64 s[6:7], s[16:17], s[6:7]
	s_mov_b64 exec, s[6:7]
	s_cbranch_execz .LBB0_1330
	s_waitcnt vmcnt(0) lgkmcnt(0)
	v_mov_b32_e32 v2, 0x22020
	ds_read_b64 v[4:5], v2
	v_readlane_b32 s6, v252, 35
	v_readlane_b32 s7, v252, 36
	v_readlane_b32 s8, v252, 39
	v_readlane_b32 s9, v252, 40
	v_mov_b32_e32 v6, 1
	s_nop 4
	global_atomic_add v6, v3, v6, s[6:7] sc0
	s_waitcnt vmcnt(0) lgkmcnt(0)
	v_cvt_f32_u32_e32 v7, v6
	v_cvt_f32_u32_e32 v8, v4
	v_add_f32_e32 v7, 0.5, v7
	v_rcp_f32_e32 v8, v8
	s_nop 1
	v_mul_f32_e32 v7, v7, v8
	v_cvt_u32_f32_e32 v7, v7
	v_mad_u32_u24 v8, v7, v4, v4
	v_mad_u32_u24 v9, v7, v5, v5
	v_add_u32_e32 v6, 1, v6
	v_cmp_eq_u32_e32 vcc, v6, v8
	s_cbranch_vccz .Lxb_poll_3
	buffer_wbl2 sc1
	s_waitcnt vmcnt(0)
	v_mov_b32_e32 v6, 1
	global_atomic_add v3, v6, s[8:9]

.LBB0_1598:
	s_load_dwordx2 s[6:7], s[0:1], 0x150
	v_readlane_b32 s4, v251, 38
	s_add_i32 s4, s4, 6
	s_waitcnt lgkmcnt(0)
	s_cmp_ge_i32 s4, s7
	s_cbranch_scc1 .LBB0_1648
	s_waitcnt vmcnt(0)
	s_barrier
	s_mov_b64 s[16:17], exec
	v_readlane_b32 s6, v251, 22
	v_readlane_b32 s7, v251, 23
	s_and_b64 s[6:7], s[16:17], s[6:7]
	s_mov_b64 exec, s[6:7]
	s_cbranch_execz .LBB0_1647
	s_waitcnt vmcnt(0) lgkmcnt(0)
	v_mov_b32_e32 v2, 0x22020
	ds_read_b64 v[4:5], v2
	v_readlane_b32 s6, v252, 35
	v_readlane_b32 s7, v252, 36
	v_readlane_b32 s8, v252, 39
	v_readlane_b32 s9, v252, 40
	v_mov_b32_e32 v6, 1
	s_nop 4
	global_atomic_add v6, v3, v6, s[6:7] sc0
	s_waitcnt vmcnt(0) lgkmcnt(0)
	v_cvt_f32_u32_e32 v7, v6
	v_cvt_f32_u32_e32 v8, v4
	v_add_f32_e32 v7, 0.5, v7
	v_rcp_f32_e32 v8, v8
	s_nop 1
	v_mul_f32_e32 v7, v7, v8
	v_cvt_u32_f32_e32 v7, v7
	v_mad_u32_u24 v8, v7, v4, v4
	v_mad_u32_u24 v9, v7, v5, v5
	v_add_u32_e32 v6, 1, v6
	v_cmp_eq_u32_e32 vcc, v6, v8
	s_cbranch_vccz .Lxb_poll_4
	buffer_wbl2 sc1
	s_waitcnt vmcnt(0)
	v_mov_b32_e32 v6, 1
	global_atomic_add v3, v6, s[8:9]

.LBB0_1682:
	s_load_dwordx2 s[6:7], s[0:1], 0x150
	v_readlane_b32 s4, v251, 38
	s_add_i32 s4, s4, 7
	s_waitcnt lgkmcnt(0)
	s_barrier
	s_cmp_ge_i32 s4, s7
	s_cbranch_scc1 .LBB0_1732
	s_waitcnt vmcnt(0)
	s_barrier
	s_mov_b64 s[16:17], exec
	v_readlane_b32 s6, v251, 22
	v_readlane_b32 s7, v251, 23
	s_and_b64 s[6:7], s[16:17], s[6:7]
	s_mov_b64 exec, s[6:7]
	s_cbranch_execz .LBB0_1731
	s_waitcnt vmcnt(0) lgkmcnt(0)
	v_mov_b32_e32 v2, 0x22020
	ds_read_b64 v[4:5], v2
	v_readlane_b32 s6, v252, 35
	v_readlane_b32 s7, v252, 36
	v_readlane_b32 s8, v252, 39
	v_readlane_b32 s9, v252, 40
	v_mov_b32_e32 v6, 1
	s_nop 4
	global_atomic_add v6, v3, v6, s[6:7] sc0
	s_waitcnt vmcnt(0) lgkmcnt(0)
	v_cvt_f32_u32_e32 v7, v6
	v_cvt_f32_u32_e32 v8, v4
	v_add_f32_e32 v7, 0.5, v7
	v_rcp_f32_e32 v8, v8
	s_nop 1
	v_mul_f32_e32 v7, v7, v8
	v_cvt_u32_f32_e32 v7, v7
	v_mad_u32_u24 v8, v7, v4, v4
	v_mad_u32_u24 v9, v7, v5, v5
	v_add_u32_e32 v6, 1, v6
	v_cmp_eq_u32_e32 vcc, v6, v8
	s_cbranch_vccz .Lxb_poll_5
	buffer_wbl2 sc1
	s_waitcnt vmcnt(0)
	v_mov_b32_e32 v6, 1
	global_atomic_add v3, v6, s[8:9]

.LBB0_2054:
	s_load_dwordx2 s[6:7], s[0:1], 0x150
	v_readlane_b32 s4, v251, 38
	s_add_i32 s4, s4, 8
	s_waitcnt lgkmcnt(0)
	s_cmp_ge_i32 s4, s7
	s_cbranch_scc1 .LBB0_2104
	s_waitcnt vmcnt(0)
	s_barrier
	s_mov_b64 s[16:17], exec
	v_readlane_b32 s6, v251, 22
	v_readlane_b32 s7, v251, 23
	s_and_b64 s[6:7], s[16:17], s[6:7]
	s_mov_b64 exec, s[6:7]
	s_cbranch_execz .LBB0_2103
	s_waitcnt vmcnt(0) lgkmcnt(0)
	v_mov_b32_e32 v2, 0x22020
	ds_read_b64 v[4:5], v2
	v_readlane_b32 s6, v252, 35
	v_readlane_b32 s7, v252, 36
	v_readlane_b32 s8, v252, 39
	v_readlane_b32 s9, v252, 40
	v_mov_b32_e32 v6, 1
	s_nop 4
	global_atomic_add v6, v3, v6, s[6:7] sc0
	s_waitcnt vmcnt(0) lgkmcnt(0)
	v_cvt_f32_u32_e32 v7, v6
	v_cvt_f32_u32_e32 v8, v4
	v_add_f32_e32 v7, 0.5, v7
	v_rcp_f32_e32 v8, v8
	s_nop 1
	v_mul_f32_e32 v7, v7, v8
	v_cvt_u32_f32_e32 v7, v7
	v_mad_u32_u24 v8, v7, v4, v4
	v_mad_u32_u24 v9, v7, v5, v5
	v_add_u32_e32 v6, 1, v6
	v_cmp_eq_u32_e32 vcc, v6, v8
	s_cbranch_vccz .Lxb_poll_6
	buffer_wbl2 sc1
	s_waitcnt vmcnt(0)
	v_mov_b32_e32 v6, 1
	global_atomic_add v3, v6, s[8:9]

.LBB0_2440:
	s_load_dwordx2 s[6:7], s[0:1], 0x150
	v_readlane_b32 s4, v251, 38
	s_add_i32 s4, s4, 9
	s_waitcnt lgkmcnt(0)
	s_cmp_ge_i32 s4, s7
	s_cbranch_scc1 .LBB0_2490
	s_waitcnt vmcnt(0)
	s_barrier
	s_mov_b64 s[16:17], exec
	v_readlane_b32 s6, v251, 22
	v_readlane_b32 s7, v251, 23
	s_and_b64 s[6:7], s[16:17], s[6:7]
	s_mov_b64 exec, s[6:7]
	s_cbranch_execz .LBB0_2489
	s_waitcnt vmcnt(0) lgkmcnt(0)
	v_mov_b32_e32 v2, 0x22020
	ds_read_b64 v[4:5], v2
	v_readlane_b32 s6, v252, 35
	v_readlane_b32 s7, v252, 36
	v_readlane_b32 s8, v252, 39
	v_readlane_b32 s9, v252, 40
	v_mov_b32_e32 v6, 1
	s_nop 4
	global_atomic_add v6, v3, v6, s[6:7] sc0
	s_waitcnt vmcnt(0) lgkmcnt(0)
	v_cvt_f32_u32_e32 v7, v6
	v_cvt_f32_u32_e32 v8, v4
	v_add_f32_e32 v7, 0.5, v7
	v_rcp_f32_e32 v8, v8
	s_nop 1
	v_mul_f32_e32 v7, v7, v8
	v_cvt_u32_f32_e32 v7, v7
	v_mad_u32_u24 v8, v7, v4, v4
	v_mad_u32_u24 v9, v7, v5, v5
	v_add_u32_e32 v6, 1, v6
	v_cmp_eq_u32_e32 vcc, v6, v8
	s_cbranch_vccz .Lxb_poll_7
	buffer_wbl2 sc1
	s_waitcnt vmcnt(0)
	v_mov_b32_e32 v6, 1
	global_atomic_add v3, v6, s[8:9]

.LBB0_2503:
	s_load_dwordx2 s[6:7], s[0:1], 0x150
	v_readlane_b32 s4, v251, 38
	s_add_i32 s4, s4, 10
	s_waitcnt lgkmcnt(0)
	s_cmp_ge_i32 s4, s7
	s_cbranch_scc1 .LBB0_2553
	s_waitcnt vmcnt(0)
	s_waitcnt vmcnt(0)
	s_barrier
	s_mov_b64 s[16:17], exec
	v_readlane_b32 s6, v251, 22
	v_readlane_b32 s7, v251, 23
	s_and_b64 s[6:7], s[16:17], s[6:7]
	s_mov_b64 exec, s[6:7]
	s_cbranch_execz .LBB0_2552
	s_waitcnt vmcnt(0) lgkmcnt(0)
	v_mov_b32_e32 v2, 0x22020
	ds_read_b64 v[4:5], v2
	v_readlane_b32 s6, v252, 35
	v_readlane_b32 s7, v252, 36
	v_readlane_b32 s8, v252, 39
	v_readlane_b32 s9, v252, 40
	v_mov_b32_e32 v6, 1
	s_nop 4
	global_atomic_add v6, v3, v6, s[6:7] sc0
	s_waitcnt vmcnt(0) lgkmcnt(0)
	v_cvt_f32_u32_e32 v7, v6
	v_cvt_f32_u32_e32 v8, v4
	v_add_f32_e32 v7, 0.5, v7
	v_rcp_f32_e32 v8, v8
	s_nop 1
	v_mul_f32_e32 v7, v7, v8
	v_cvt_u32_f32_e32 v7, v7
	v_mad_u32_u24 v8, v7, v4, v4
	v_mad_u32_u24 v9, v7, v5, v5
	v_add_u32_e32 v6, 1, v6
	v_cmp_eq_u32_e32 vcc, v6, v8
	s_cbranch_vccz .Lxb_poll_8
	buffer_wbl2 sc1
	s_waitcnt vmcnt(0)
	v_mov_b32_e32 v6, 1
	global_atomic_add v3, v6, s[8:9]

.LBB0_2909:
	s_load_dwordx2 s[6:7], s[0:1], 0x150
	v_readlane_b32 s4, v251, 38
	s_add_i32 s4, s4, 11
	s_waitcnt lgkmcnt(0)
	s_cmp_ge_i32 s4, s7
	s_cbranch_scc1 .LBB0_2959
	s_waitcnt vmcnt(0)
	s_waitcnt vmcnt(0)
	s_barrier
	s_mov_b64 s[16:17], exec
	v_readlane_b32 s6, v251, 22
	v_readlane_b32 s7, v251, 23
	s_and_b64 s[6:7], s[16:17], s[6:7]
	s_mov_b64 exec, s[6:7]
	s_cbranch_execz .LBB0_2958
	s_waitcnt vmcnt(0) lgkmcnt(0)
	v_mov_b32_e32 v2, 0x22020
	ds_read_b64 v[4:5], v2
	v_readlane_b32 s6, v252, 35
	v_readlane_b32 s7, v252, 36
	v_readlane_b32 s8, v252, 39
	v_readlane_b32 s9, v252, 40
	v_mov_b32_e32 v6, 1
	s_nop 4
	global_atomic_add v6, v3, v6, s[6:7] sc0
	s_waitcnt vmcnt(0) lgkmcnt(0)
	v_cvt_f32_u32_e32 v7, v6
	v_cvt_f32_u32_e32 v8, v4
	v_add_f32_e32 v7, 0.5, v7
	v_rcp_f32_e32 v8, v8
	s_nop 1
	v_mul_f32_e32 v7, v7, v8
	v_cvt_u32_f32_e32 v7, v7
	v_mad_u32_u24 v8, v7, v4, v4
	v_mad_u32_u24 v9, v7, v5, v5
	v_add_u32_e32 v6, 1, v6
	v_cmp_eq_u32_e32 vcc, v6, v8
	s_cbranch_vccz .Lxb_poll_9
	buffer_wbl2 sc1
	s_waitcnt vmcnt(0)
	v_mov_b32_e32 v6, 1
	global_atomic_add v3, v6, s[8:9]

.LBB0_2973:
	s_or_b64 exec, exec, s[16:17]
	s_load_dwordx2 s[6:7], s[0:1], 0x150
	v_readlane_b32 s4, v251, 38
	s_add_i32 s4, s4, 12
	s_waitcnt lgkmcnt(0)
	s_cmp_ge_i32 s4, s7
	s_cbranch_scc1 .LBB0_3023
	s_waitcnt vmcnt(0)
	s_barrier
	s_mov_b64 s[16:17], exec
	v_readlane_b32 s6, v251, 22
	v_readlane_b32 s7, v251, 23
	s_and_b64 s[6:7], s[16:17], s[6:7]
	s_mov_b64 exec, s[6:7]
	s_cbranch_execz .LBB0_3022
	s_waitcnt vmcnt(0) lgkmcnt(0)
	v_mov_b32_e32 v2, 0x22020
	ds_read_b64 v[4:5], v2
	v_readlane_b32 s6, v252, 35
	v_readlane_b32 s7, v252, 36
	v_readlane_b32 s8, v252, 39
	v_readlane_b32 s9, v252, 40
	v_mov_b32_e32 v6, 1
	s_nop 4
	global_atomic_add v6, v3, v6, s[6:7] sc0
	s_waitcnt vmcnt(0) lgkmcnt(0)
	v_cvt_f32_u32_e32 v7, v6
	v_cvt_f32_u32_e32 v8, v4
	v_add_f32_e32 v7, 0.5, v7
	v_rcp_f32_e32 v8, v8
	s_nop 1
	v_mul_f32_e32 v7, v7, v8
	v_cvt_u32_f32_e32 v7, v7
	v_mad_u32_u24 v8, v7, v4, v4
	v_mad_u32_u24 v9, v7, v5, v5
	v_add_u32_e32 v6, 1, v6
	v_cmp_eq_u32_e32 vcc, v6, v8
	s_cbranch_vccz .Lxb_poll_10
	buffer_wbl2 sc1
	s_waitcnt vmcnt(0)
	v_mov_b32_e32 v6, 1
	global_atomic_add v3, v6, s[8:9]

.Lxb_to100:
	s_getpc_b64 s[98:99]

.LBB0_3055:
	s_waitcnt vmcnt(0) lgkmcnt(0)
	v_mov_b32_e32 v2, 0x22020
	ds_read_b64 v[4:5], v2
	v_readlane_b32 s6, v252, 35
	v_readlane_b32 s7, v252, 36
	v_readlane_b32 s8, v252, 39
	v_readlane_b32 s9, v252, 40
	v_mov_b32_e32 v6, 1
	s_nop 4
	global_atomic_add v6, v3, v6, s[6:7] sc0
	s_waitcnt vmcnt(0) lgkmcnt(0)
	v_cvt_f32_u32_e32 v7, v6
	v_cvt_f32_u32_e32 v8, v4
	v_add_f32_e32 v7, 0.5, v7
	v_rcp_f32_e32 v8, v8
	s_nop 1
	v_mul_f32_e32 v7, v7, v8
	v_cvt_u32_f32_e32 v7, v7
	v_mad_u32_u24 v8, v7, v4, v4
	v_mad_u32_u24 v9, v7, v5, v5
	v_add_u32_e32 v6, 1, v6
	v_cmp_eq_u32_e32 vcc, v6, v8
	s_cbranch_vccz .Lxb_poll_99
	buffer_wbl2 sc1
	s_waitcnt vmcnt(0)
	v_mov_b32_e32 v6, 1
	global_atomic_add v3, v6, s[8:9]

.Lxb_done_99:
	buffer_inv sc1
	s_waitcnt vmcnt(0)
	s_branch .Lxb_to100
